# P0 row balance: item waves take an 8th row only for 12 of every 22 (was 15), every non-item wave takes 9 rows
# speedup vs baseline: 1.0007x; 1.0007x over previous
; __device__ __forceinline__ void p0_prologue(const Args& a, LAS unsigned char* lds, int vcu, int G, int wave, int lane) {
;     ...
;     const bool bal = (NGW == 2048) && (M == 16384); const bool item_wave = gw < I_IN + I_PP; const int w2 = gw - (I_IN + I_PP);
;     const int nrows = !bal ? (M - gw + NGW - 1) / NGW : 7 + (item_wave ? ((gw % 22) < 15 ? 1 : 0) : (w2 + 640 < 1088 ? 2 : 1));
.LBB0_34:
	s_or_b64 exec, exec, s[6:7]
	s_cmpk_lg_i32 s33, 0x100
	s_cselect_b64 s[6:7], -1, 0
	s_cmpk_eq_i32 s33, 0x100
	s_cbranch_scc0 .LBB0_37
	s_and_b64 vcc, exec, s[0:1]
	s_cbranch_vccz .LBB0_38
	s_cmpk_lt_u32 s3, 0x800
	s_cselect_b32 s8, 2, 1
	s_cbranch_execz .LBB0_39
	s_branch .LBB0_40

; __device__ __forceinline__ void p0_prologue(const Args& a, LAS unsigned char* lds, int vcu, int G, int wave, int lane) {
;     ...
;     const int nrows = !bal ? (M - gw + NGW - 1) / NGW : 7 + (item_wave ? ((gw % 22) < 15 ? 1 : 0) : (w2 + 640 < 1088 ? 2 : 1));
.LBB0_38:
.LBB0_39:
	s_mul_hi_i32 s0, s3, 0x2e8ba2e9
	s_lshr_b32 s1, s0, 31
	s_ashr_i32 s0, s0, 2
	s_add_i32 s0, s0, s1
	s_mul_i32 s0, s0, 22
	s_sub_i32 s0, s3, s0
	s_cmp_lt_i32 s0, 12
	s_cselect_b64 s[0:1], -1, 0
	v_cndmask_b32_e64 v2, 0, 1, s[0:1]
	s_nop 0
	v_readfirstlane_b32 s8, v2

; #define GAS __attribute__((address_space(1)))
; __device__ __forceinline__ void p0_prologue(const Args& a, LAS unsigned char* lds, int vcu, int G, int wave, int lane) {
;     ...
;     for (int i = 0; i < nrows; ++i) {
;         const int m = (!bal || i < 7) ? gw + NGW * i : (item_wave ? 15424 + (gw / 22) * 15 + gw % 22 : 14336 + w2 + 640 * (i - 7));
;         const GAS f32x4* xr = (const GAS f32x4*)(x + (size_t)m * DM) + lane;
.LBB0_42:
	s_cmp_lt_i32 s12, 1
	s_cbranch_scc1 .LBB0_49
	s_add_u32 s13, s22, 0x1c80000
	s_mul_hi_i32 s0, s3, 0x2e8ba2e9
	s_addc_u32 s15, s23, 0
	s_lshr_b32 s1, s0, 31
	s_ashr_i32 s0, s0, 2
	s_add_i32 s0, s0, s1
	s_mul_i32 s1, s0, 12
	s_mul_i32 s0, s0, 22
	s_sub_i32 s0, s3, s0
	v_mov_b32_e32 v3, 0
	s_add_i32 s16, s0, s1
	v_lshlrev_b32_e32 v2, 4, v206
	v_lshlrev_b32_e32 v10, 3, v206
	v_mov_b32_e32 v11, v3
	s_addk_i32 s16, 0x3d00
	s_mov_b32 s17, 0
	v_cmp_eq_u32_e64 s[0:1], 0, v206
	v_lshl_add_u64 v[4:5], s[60:61], 0, v[2:3]
	v_lshl_add_u64 v[6:7], s[20:21], 0, v[10:11]
	v_lshl_add_u64 v[8:9], s[62:63], 0, v[2:3]
	v_lshl_add_u64 v[10:11], s[96:97], 0, v[10:11]
	s_add_i32 s24, s3, 0x2100
	s_branch .LBB0_45
